# MoBA: per-step compute test evaluated once, single v_add3 QK base
# baseline (speedup 1.0000x reference)
.LBB0_148:
	s_cmp_ge_i32 s16, s48
	s_cselect_b64 s[8:9], -1, 0
	s_mov_b64 s[80:81], s[0:1]
	s_ashr_i32 s0, s51, 1
	s_sub_i32 s0, s47, s0
	s_lshl_b32 s0, 1, s0
	s_and_b32 s1, s0, s49
	s_cmp_lg_u32 s1, 0
	s_cbranch_scc1 .Lmg_qk
	s_and_b64 vcc, exec, s[8:9]
	s_cbranch_vccnz .LBB0_137
	s_xor_b32 s10, s15, 1
	s_mul_i32 s10, s10, 0x11000
	s_add_i32 s10, s10, 0
	v_add3_u32 v85, s10, v165, v216
	v_add3_u32 v84, s10, v0, v216
	v_add_u32_e32 v86, 0x8800, v85
	s_waitcnt vmcnt(7)
	ds_write_b128 v84, v[4:7]
	s_waitcnt vmcnt(6)
	ds_write2_b64 v86, v[8:9], v[10:11] offset1:2
	s_waitcnt vmcnt(5)
	ds_write_b128 v84, v[12:15] offset:8704
	v_add_u32_e32 v86, 0xa800, v85
	s_waitcnt vmcnt(4)
	ds_write2_b64 v86, v[16:17], v[18:19] offset0:64 offset1:66
	s_waitcnt vmcnt(3)
	ds_write_b128 v84, v[20:23] offset:17408
	v_add_u32_e32 v86, 0xc800, v85
	s_waitcnt vmcnt(2)
	ds_write2_b64 v86, v[24:25], v[26:27] offset0:128 offset1:130
	s_waitcnt vmcnt(1)
	ds_write_b128 v84, v[28:31] offset:26112
	v_add_u32_e32 v84, 0xe800, v85
	s_andn2_b64 vcc, exec, s[80:81]
	s_waitcnt vmcnt(0)
	ds_write2_b64 v84, v[32:33], v[34:35] offset0:192 offset1:194
	s_cbranch_vccnz .LBB0_137
	s_lshr_b32 s0, s14, 1
	s_sub_i32 s0, s47, s0
	s_lshl_b32 s1, s14, 7
	s_lshl_b32 s0, s0, 8
	s_and_b32 s1, s1, 0x80
	s_or_b32 s0, s0, s1
	s_ashr_i32 s1, s0, 31
	v_lshl_add_u64 v[4:5], v[140:141], 0, s[0:1]
	v_mov_b64_e32 v[6:7], s[88:89]
	v_lshl_add_u64 v[28:29], s[0:1], 1, v[118:119]
	v_mad_u64_u32 v[6:7], s[0:1], v4, s72, v[6:7]
	v_mad_i32_i24 v7, v5, s72, v7
	v_lshl_add_u64 v[4:5], v[6:7], 0, s[20:21]
	v_lshl_add_u64 v[30:31], v[4:5], 0, v[2:3]
	v_add_co_u32_e32 v4, vcc, s3, v30
	s_mov_b32 s0, 0x3d000
	s_nop 0
	v_addc_co_u32_e32 v5, vcc, 0, v31, vcc
	v_add_co_u32_e32 v12, vcc, s0, v30
	v_lshl_add_u64 v[8:9], v[28:29], 0, v[146:147]
	s_nop 0
	v_addc_co_u32_e32 v13, vcc, 0, v31, vcc
	v_add_co_u32_e32 v20, vcc, 0x79000, v30
	v_lshl_add_u64 v[16:17], v[28:29], 0, v[148:149]
	s_nop 0
	v_addc_co_u32_e32 v21, vcc, 0, v31, vcc
	v_add_co_u32_e32 v30, vcc, 0xb5000, v30
	v_lshl_add_u64 v[24:25], v[28:29], 0, v[150:151]
	s_nop 0
	v_addc_co_u32_e32 v31, vcc, 0, v31, vcc
	v_lshl_add_u64 v[32:33], v[28:29], 0, v[152:153]
	global_load_dwordx4 v[4:7], v[4:5], off offset:1024
	s_nop 0
	global_load_dwordx4 v[8:11], v[8:9], off
	s_nop 0
	global_load_dwordx4 v[12:15], v[12:13], off offset:1024
	s_nop 0
	global_load_dwordx4 v[16:19], v[16:17], off
	s_nop 0
	global_load_dwordx4 v[20:23], v[20:21], off offset:1024
	s_nop 0
	global_load_dwordx4 v[24:27], v[24:25], off
	s_nop 0
	global_load_dwordx4 v[28:31], v[30:31], off offset:1024
	s_nop 0
	global_load_dwordx4 v[32:35], v[32:33], off
	s_branch .LBB0_137

.Lmg_qk:
	s_mul_i32 s1, s15, 0x11000
	s_add_i32 s1, s1, 0
	v_add3_u32 v195, s1, v158, v167
	ds_read_b128 v[108:111], v195
	ds_read_b128 v[104:107], v195 offset:64
	ds_read_b128 v[100:103], v195 offset:128
	ds_read_b128 v[96:99], v195 offset:192
	ds_read_b128 v[92:95], v195 offset:272
	ds_read_b128 v[88:91], v195 offset:336
	ds_read_b128 v[84:87], v195 offset:400
	ds_read_b128 v[198:201], v195 offset:464
	ds_read_b128 v[202:205], v195 offset:8704
	ds_read_b128 v[206:209], v195 offset:8768
	ds_read_b128 v[230:233], v195 offset:8832
	ds_read_b128 v[234:237], v195 offset:8896
	ds_read_b128 v[238:241], v195 offset:8976
	ds_read_b128 v[242:245], v195 offset:9040
	ds_read_b128 v[246:249], v195 offset:9104
	s_waitcnt lgkmcnt(11)
	v_mfma_f32_16x16x32_bf16 v[112:115], v[108:111], v[36:39], 0
	v_mfma_f32_16x16x32_bf16 v[112:115], v[104:107], v[40:43], v[112:115]
	v_mfma_f32_16x16x32_bf16 v[112:115], v[100:103], v[44:47], v[112:115]
	v_mfma_f32_16x16x32_bf16 v[112:115], v[96:99], v[48:51], v[112:115]
	ds_read_b128 v[96:99], v195 offset:9168
	s_waitcnt lgkmcnt(8)
	v_mfma_f32_16x16x32_bf16 v[108:111], v[92:95], v[36:39], 0
	v_mfma_f32_16x16x32_bf16 v[108:111], v[88:91], v[40:43], v[108:111]
	v_mfma_f32_16x16x32_bf16 v[108:111], v[84:87], v[44:47], v[108:111]
	v_mfma_f32_16x16x32_bf16 v[108:111], v[198:201], v[48:51], v[108:111]
	ds_read_b128 v[92:95], v195 offset:17408
	ds_read_b128 v[88:91], v195 offset:17472
	ds_read_b128 v[84:87], v195 offset:17536
	ds_read_b128 v[198:201], v195 offset:17600
	s_waitcnt lgkmcnt(8)
	v_mfma_f32_16x16x32_bf16 v[104:107], v[202:205], v[36:39], 0
	v_mfma_f32_16x16x32_bf16 v[104:107], v[206:209], v[40:43], v[104:107]
	v_mfma_f32_16x16x32_bf16 v[104:107], v[230:233], v[44:47], v[104:107]
	v_mfma_f32_16x16x32_bf16 v[104:107], v[234:237], v[48:51], v[104:107]
	ds_read_b128 v[202:205], v195 offset:17680
	ds_read_b128 v[206:209], v195 offset:17744
	ds_read_b128 v[230:233], v195 offset:17808
	ds_read_b128 v[234:237], v195 offset:17872
	s_waitcnt lgkmcnt(8)
	v_mfma_f32_16x16x32_bf16 v[100:103], v[238:241], v[36:39], 0
	v_mfma_f32_16x16x32_bf16 v[100:103], v[242:245], v[40:43], v[100:103]
	v_mfma_f32_16x16x32_bf16 v[100:103], v[246:249], v[44:47], v[100:103]
	v_mfma_f32_16x16x32_bf16 v[100:103], v[96:99], v[48:51], v[100:103]
	ds_read_b128 v[238:241], v195 offset:26112
	ds_read_b128 v[242:245], v195 offset:26176
	ds_read_b128 v[246:249], v195 offset:26240
	s_waitcnt lgkmcnt(7)
	v_mfma_f32_16x16x32_bf16 v[96:99], v[92:95], v[36:39], 0
	v_mfma_f32_16x16x32_bf16 v[96:99], v[88:91], v[40:43], v[96:99]
	v_mfma_f32_16x16x32_bf16 v[96:99], v[84:87], v[44:47], v[96:99]
	v_mfma_f32_16x16x32_bf16 v[96:99], v[198:201], v[48:51], v[96:99]
	ds_read_b128 v[198:201], v195 offset:26304
	s_waitcnt lgkmcnt(4)
	v_mfma_f32_16x16x32_bf16 v[92:95], v[202:205], v[36:39], 0
	v_mfma_f32_16x16x32_bf16 v[92:95], v[206:209], v[40:43], v[92:95]
	v_mfma_f32_16x16x32_bf16 v[92:95], v[230:233], v[44:47], v[92:95]
	v_mfma_f32_16x16x32_bf16 v[92:95], v[234:237], v[48:51], v[92:95]
	ds_read_b128 v[202:205], v195 offset:26384
	ds_read_b128 v[206:209], v195 offset:26448
	ds_read_b128 v[230:233], v195 offset:26512
	ds_read_b128 v[234:237], v195 offset:26576
	s_waitcnt lgkmcnt(4)
	v_mfma_f32_16x16x32_bf16 v[88:91], v[238:241], v[36:39], 0
	v_mfma_f32_16x16x32_bf16 v[88:91], v[242:245], v[40:43], v[88:91]
	v_mfma_f32_16x16x32_bf16 v[88:91], v[246:249], v[44:47], v[88:91]
	v_mfma_f32_16x16x32_bf16 v[88:91], v[198:201], v[48:51], v[88:91]
	s_waitcnt lgkmcnt(0)
	v_mfma_f32_16x16x32_bf16 v[84:87], v[202:205], v[36:39], 0
	v_mfma_f32_16x16x32_bf16 v[84:87], v[206:209], v[40:43], v[84:87]
	v_mfma_f32_16x16x32_bf16 v[84:87], v[230:233], v[44:47], v[84:87]
	v_mfma_f32_16x16x32_bf16 v[84:87], v[234:237], v[48:51], v[84:87]
	ds_read_b128 v[202:205], v195 offset:34816
	ds_read_b128 v[206:209], v195 offset:35088
	ds_read_b128 v[230:233], v195 offset:43520
	ds_read_b128 v[234:237], v195 offset:43792
	v_and_b32_e32 v197, s0, v139
	v_cmp_eq_u32_e64 s[0:1], 0, v197
	s_cmp_lt_u32 s51, 2
	s_mov_b64 s[10:11], -1
	s_cbranch_scc1 .LBB0_154
	v_max3_f32 v197, v112, v113, v114
	v_max3_f32 v198, v96, v97, v98
	v_max3_f32 v197, v197, v115, v108
	v_max3_f32 v198, v198, v99, v92
	v_max3_f32 v197, v197, v109, v110
	v_max3_f32 v198, v198, v93, v94
	v_max3_f32 v197, v197, v111, v104
	v_max3_f32 v198, v198, v95, v88
	v_max3_f32 v197, v197, v105, v106
	v_max3_f32 v198, v198, v89, v90
	v_max3_f32 v197, v197, v107, v100
	v_max3_f32 v198, v198, v91, v84
	v_max3_f32 v197, v197, v101, v102
	v_max3_f32 v198, v198, v85, v86
	v_max_f32_e32 v197, v197, v103
	v_max_f32_e32 v198, v198, v87
	v_max_f32_e32 v197, v197, v198
	v_cndmask_b32_e64 v197, v197, v215, s[0:1]
	s_mov_b64 s[10:11], 0
